# row rstd for P3/P6 epilogues from an LDS table computed once per phase (5 row panels per workgroup) instead of 8 global loads + shuffles + rsq per unit
# speedup vs baseline: 1.0184x; 1.0115x over previous
.LBB0_303:
	s_cmp_lt_i32 s60, 4
	s_cselect_b64 s[6:7], -1, 0
	s_and_b64 s[8:9], s[6:7], s[4:5]
	s_andn2_b64 vcc, exec, s[8:9]
	s_cbranch_vccnz .LBB0_332
	s_cmpk_gt_i32 s2, 0xeff
	s_cbranch_scc1 .LBB0_332
	v_mbcnt_hi_u32_b32 v0, -1, v228
	v_lshl_add_u32 v0, s71, 6, v0
	s_and_b32 s98, s2, 7
	s_lshr_b32 s99, s2, 3
	s_and_b32 s99, s99, 7
	s_mul_i32 s98, s98, 40
	s_add_u32 s98, s98, s99
	s_lshl_b32 s98, s98, 8
	s_add_u32 s100, s30, 0x2c00000
	s_addc_u32 s101, s31, 0
	v_mov_b32_e32 v60, 0x358637bd
	v_add_u32_e32 v1, 0, v0
	v_lshrrev_b32_e32 v2, 8, v1
	v_lshlrev_b32_e32 v2, 11, v2
	v_and_b32_e32 v3, 0xff, v1
	v_add3_u32 v2, v2, v3, s98
	v_lshlrev_b32_e32 v2, 6, v2
	global_load_dwordx4 v[4:7], v2, s[100:101] offset:0
	global_load_dwordx4 v[8:11], v2, s[100:101] offset:16
	global_load_dwordx4 v[12:15], v2, s[100:101] offset:32
	global_load_dwordx4 v[16:19], v2, s[100:101] offset:48
	v_add_u32_e32 v21, 512, v0
	v_lshrrev_b32_e32 v22, 8, v21
	v_lshlrev_b32_e32 v22, 11, v22
	v_and_b32_e32 v23, 0xff, v21
	v_add3_u32 v22, v22, v23, s98
	v_lshlrev_b32_e32 v22, 6, v22
	global_load_dwordx4 v[24:27], v22, s[100:101] offset:0
	global_load_dwordx4 v[28:31], v22, s[100:101] offset:16
	global_load_dwordx4 v[32:35], v22, s[100:101] offset:32
	global_load_dwordx4 v[36:39], v22, s[100:101] offset:48
	s_cmp_lt_u32 s71, 4
	s_cbranch_scc0 .Lrs_skip_2c00000
	v_add_u32_e32 v41, 1024, v0
	v_lshrrev_b32_e32 v42, 8, v41
	v_lshlrev_b32_e32 v42, 11, v42
	v_and_b32_e32 v43, 0xff, v41
	v_add3_u32 v42, v42, v43, s98
	v_lshlrev_b32_e32 v42, 6, v42
	global_load_dwordx4 v[44:47], v42, s[100:101] offset:0
	global_load_dwordx4 v[48:51], v42, s[100:101] offset:16
	global_load_dwordx4 v[52:55], v42, s[100:101] offset:32
	global_load_dwordx4 v[56:59], v42, s[100:101] offset:48
.Lrs_skip_2c00000:
	s_waitcnt vmcnt(0)
	v_add_f32_e32 v4, v4, v5
	v_add_f32_e32 v6, v6, v7
	v_add_f32_e32 v4, v4, v6
	v_add_f32_e32 v8, v8, v9
	v_add_f32_e32 v10, v10, v11
	v_add_f32_e32 v8, v8, v10
	v_add_f32_e32 v12, v12, v13
	v_add_f32_e32 v14, v14, v15
	v_add_f32_e32 v12, v12, v14
	v_add_f32_e32 v16, v16, v17
	v_add_f32_e32 v18, v18, v19
	v_add_f32_e32 v16, v16, v18
	v_add_f32_e32 v4, v4, v8
	v_add_f32_e32 v12, v12, v16
	v_add_f32_e32 v4, v4, v12
	v_fmamk_f32 v4, v4, 0x3a800000, v60
	v_rsq_f32_e32 v4, v4
	v_lshlrev_b32_e32 v2, 2, v1
	v_add_u32_e32 v2, 0x20800, v2
	ds_write_b32 v2, v4
	s_waitcnt vmcnt(0)
	v_add_f32_e32 v24, v24, v25
	v_add_f32_e32 v26, v26, v27
	v_add_f32_e32 v24, v24, v26
	v_add_f32_e32 v28, v28, v29
	v_add_f32_e32 v30, v30, v31
	v_add_f32_e32 v28, v28, v30
	v_add_f32_e32 v32, v32, v33
	v_add_f32_e32 v34, v34, v35
	v_add_f32_e32 v32, v32, v34
	v_add_f32_e32 v36, v36, v37
	v_add_f32_e32 v38, v38, v39
	v_add_f32_e32 v36, v36, v38
	v_add_f32_e32 v24, v24, v28
	v_add_f32_e32 v32, v32, v36
	v_add_f32_e32 v24, v24, v32
	v_fmamk_f32 v24, v24, 0x3a800000, v60
	v_rsq_f32_e32 v24, v24
	v_lshlrev_b32_e32 v22, 2, v21
	v_add_u32_e32 v22, 0x20800, v22
	ds_write_b32 v22, v24
	s_cmp_lt_u32 s71, 4
	s_cbranch_scc0 .Lrs_done_2c00000
	s_waitcnt vmcnt(0)
	v_add_f32_e32 v44, v44, v45
	v_add_f32_e32 v46, v46, v47
	v_add_f32_e32 v44, v44, v46
	v_add_f32_e32 v48, v48, v49
	v_add_f32_e32 v50, v50, v51
	v_add_f32_e32 v48, v48, v50
	v_add_f32_e32 v52, v52, v53
	v_add_f32_e32 v54, v54, v55
	v_add_f32_e32 v52, v52, v54
	v_add_f32_e32 v56, v56, v57
	v_add_f32_e32 v58, v58, v59
	v_add_f32_e32 v56, v56, v58
	v_add_f32_e32 v44, v44, v48
	v_add_f32_e32 v52, v52, v56
	v_add_f32_e32 v44, v44, v52
	v_fmamk_f32 v44, v44, 0x3a800000, v60
	v_rsq_f32_e32 v44, v44
	v_lshlrev_b32_e32 v42, 2, v41
	v_add_u32_e32 v42, 0x20800, v42
	ds_write_b32 v42, v44
.Lrs_done_2c00000:
	s_waitcnt lgkmcnt(0)
	s_add_u32 s70, s30, 0x1200000
	s_mov_b32 s4, s71
	v_mbcnt_hi_u32_b32 v9, -1, v228
	s_addc_u32 s71, s31, 0
	s_lshl_b32 s72, s4, 10
	v_lshlrev_b32_e32 v14, 4, v9
	v_add_u32_e32 v0, s72, v14
	s_waitcnt lgkmcnt(0)
	v_add_u32_e32 v1, 0x2000, v0
	v_ashrrev_i32_e32 v2, 31, v1
	v_lshrrev_b32_e32 v2, 22, v2
	v_add_u32_e32 v2, v1, v2
	v_ashrrev_i32_e32 v8, 10, v2
	v_mul_i32_i24_e32 v2, 0x400, v8
	v_sub_u32_e32 v1, v1, v2
	v_lshrrev_b32_e32 v2, 4, v1
	v_bitop3_b32 v1, v2, v1, 32 bitop3:0x6c
	v_ashrrev_i32_e32 v2, 31, v1
	v_lshrrev_b32_e32 v2, 26, v2
	v_add_u32_e32 v2, v1, v2
	v_ashrrev_i32_e32 v10, 6, v2
	v_lshlrev_b32_e32 v3, 3, v8
	v_and_b32_e32 v2, 0xffc0, v2
	v_and_b32_e32 v3, -16, v3
	v_sub_u32_e32 v1, v1, v2
	v_add_u32_e32 v3, v10, v3
	v_lshrrev_b16_e32 v2, 7, v1
	v_and_b32_e32 v4, 3, v10
	s_mov_b32 s4, 0x1fffe0
	v_lshrrev_b32_e32 v5, 2, v3
	v_lshlrev_b32_e32 v6, 1, v3
	v_and_b32_e32 v2, 1, v2
	v_and_or_b32 v4, v3, s4, v4
	v_and_b32_e32 v5, 4, v5
	v_and_b32_e32 v6, 24, v6
	v_add_u16_e32 v1, v1, v2
	v_mov_b32_e32 v2, 1
	v_or3_b32 v4, v4, v5, v6
	v_lshlrev_b32_e32 v5, 5, v8
	v_ashrrev_i16_sdwa v1, v2, sext(v1) dst_sel:DWORD dst_unused:UNUSED_PAD src0_sel:DWORD src1_sel:BYTE_0
	v_and_b32_e32 v5, 32, v5
	v_bfe_i32 v11, v1, 0, 16
	v_add_lshl_u32 v1, v5, v11, 1
	v_lshl_add_u32 v144, v4, 11, v1
	v_lshl_add_u32 v146, v3, 11, v1
	v_ashrrev_i32_e32 v1, 31, v0
	v_lshrrev_b32_e32 v1, 22, v1
	v_add_u32_e32 v1, v0, v1
	v_ashrrev_i32_e32 v12, 10, v1
	v_mul_i32_i24_e32 v1, 0x400, v12
	v_sub_u32_e32 v0, v0, v1
	v_lshrrev_b32_e32 v1, 4, v0
	v_bitop3_b32 v0, v1, v0, 32 bitop3:0x6c
	v_ashrrev_i32_e32 v1, 31, v0
	v_lshrrev_b32_e32 v1, 26, v1
	v_add_u32_e32 v1, v0, v1
	v_lshlrev_b32_e32 v3, 3, v12
	v_ashrrev_i32_e32 v13, 6, v1
	v_and_b32_e32 v3, -16, v3
	v_add_u32_e32 v3, v13, v3
	v_and_b32_e32 v4, 3, v13
	s_ashr_i32 s73, s2, 31
	v_and_or_b32 v4, v3, s4, v4
	s_lshr_b32 s4, s73, 29
	s_add_i32 s4, s2, s4
	s_ashr_i32 s6, s4, 3
	s_and_b32 s4, s4, -8
	s_lshr_b32 s5, s3, 8
	s_sub_i32 s4, s2, s4
	s_cmp_lt_i32 s4, 0
	s_movk_i32 s74, 0x1e1
	s_cselect_b32 s7, s74, 0x1e0
	s_mul_i32 s4, s4, s7
	s_add_i32 s4, s4, s6
	s_mul_hi_i32 s6, s4, 0x2aaaaaab
	s_lshr_b32 s7, s6, 31
	s_ashr_i32 s6, s6, 4
	s_add_i32 s6, s6, s7
	s_lshl_b32 s7, s6, 3
	s_mulk_i32 s6, 0x60
	s_sub_i32 s6, s4, s6
	s_bfe_i32 s4, s6, 0x80000
	s_bfe_u32 s4, s4, 0x3000c
	s_add_i32 s10, s6, s4
	s_bfe_i32 s4, s10, 0x80000
	s_and_b32 s10, s10, 0xf8
	s_sub_i32 s6, s6, s10
	s_sext_i32_i16 s4, s4
	s_sext_i32_i8 s6, s6
	v_lshrrev_b32_e32 v5, 2, v3
	v_lshlrev_b32_e32 v6, 1, v3
	v_and_b32_e32 v1, 0xc0, v1
	s_lshr_b32 s4, s4, 3
	s_add_i32 s50, s7, s6
	v_and_b32_e32 v5, 4, v5
	v_and_b32_e32 v6, 24, v6
	v_sub_u32_e32 v0, v0, v1
	s_ashr_i32 s51, s50, 31
	s_bfe_i64 s[10:11], s[4:5], 0x100000
	v_or3_b32 v4, v4, v5, v6
	v_lshlrev_b32_e32 v5, 5, v12
	v_ashrrev_i16_sdwa v0, v2, sext(v0) dst_sel:DWORD dst_unused:UNUSED_PAD src0_sel:DWORD src1_sel:BYTE_0
	s_lshl_b64 s[6:7], s[50:51], 19
	s_lshl_b64 s[10:11], s[10:11], 19
	v_and_b32_e32 v5, 32, v5
	v_bfe_i32 v15, v0, 0, 16
	s_add_u32 s54, s70, s10
	v_add_lshl_u32 v0, v5, v15, 1
	s_addc_u32 s55, s71, s11
	s_add_i32 s75, s72, 0
	v_lshl_add_u32 v148, v4, 11, v0
	s_add_i32 m0, s75, 0x10000
	v_lshl_add_u32 v150, v3, 11, v0
	global_load_lds_dwordx4 v148, s[54:55]
	s_add_i32 m0, s75, 0x12000
	s_add_u32 s10, s54, 0x40000
	global_load_lds_dwordx4 v144, s[54:55]
	s_addc_u32 s11, s55, 0
	s_add_i32 m0, s75, 0x14000
	v_mov_b32_e32 v153, 0
	global_load_lds_dwordx4 v148, s[10:11]
	s_add_i32 m0, s75, 0x16000
	s_add_u32 s52, s62, s6
	s_addc_u32 s53, s63, s7
	s_add_i32 s76, s75, 0x2000
	global_load_lds_dwordx4 v144, s[10:11]
	s_mov_b32 m0, s75
	s_add_u32 s6, s52, 0x40000
	global_load_lds_dwordx4 v150, s[52:53]
	s_mov_b32 m0, s76
	s_addc_u32 s7, s53, 0
	s_add_i32 s77, s75, 0x4000
	global_load_lds_dwordx4 v146, s[52:53]
	s_mov_b32 m0, s77
	s_add_i32 s78, s75, 0x6000
	global_load_lds_dwordx4 v150, s[6:7]
	s_mov_b32 m0, s78
	v_mov_b32_e32 v149, v153
	global_load_lds_dwordx4 v146, s[6:7]
	v_mov_b32_e32 v145, v153
	v_mov_b32_e32 v151, v153
	v_mov_b32_e32 v147, v153
	s_cmp_eq_u32 s5, 1
	v_writelane_b32 v254, s90, 11
	s_mov_b32 s11, 0
	v_lshl_add_u64 v[6:7], s[54:55], 0, v[148:149]
	v_lshl_add_u64 v[2:3], s[54:55], 0, v[144:145]
	v_lshl_add_u64 v[0:1], s[52:53], 0, v[150:151]
	s_cselect_b64 s[26:27], -1, 0
	s_cmp_lg_u32 s5, 1
	v_lshl_add_u64 v[4:5], s[52:53], 0, v[146:147]
	v_writelane_b32 v254, s91, 12
	s_cbranch_scc1 .LBB0_307
	s_barrier

.LBB0_316:
	s_mul_i32 s98, s50, 0x667
	s_lshr_b32 s98, s98, 16
	s_mul_i32 s98, s98, 40
	s_sub_u32 s98, s50, s98
	s_lshr_b32 s98, s98, 3
	s_lshl_b32 s98, s98, 10
	s_add_u32 s98, s98, 0x20800
	v_add_u32_e32 v139, s81, v155
	v_lshl_add_u32 v139, v139, 2, s98
	ds_read_b32 v128, v139 offset:0
	ds_read_b32 v129, v139 offset:64
	ds_read_b32 v130, v139 offset:192
	ds_read_b32 v131, v139 offset:512
	ds_read_b32 v132, v139 offset:640
	ds_read_b32 v133, v139 offset:128
	ds_read_b32 v134, v139 offset:576
	ds_read_b32 v135, v139 offset:704
	s_waitcnt lgkmcnt(0)
	s_lshl_b32 s10, s50, 8
	s_add_i32 s52, s10, s81
	v_or_b32_e32 v136, s52, v155
	v_or_b32_e32 v188, 16, v136
	v_or_b32_e32 v142, 32, v136
	v_or_b32_e32 v140, 48, v136
	v_ashrrev_i32_e32 v137, 31, v136
	s_nop 0
	s_nop 0
	s_nop 0
	v_add_u32_e32 v138, 0x80, v136
	s_nop 0
	s_cmp_gt_i32 s66, 3
	s_mov_b64 s[54:55], -1
	s_waitcnt lgkmcnt(4)
	s_waitcnt lgkmcnt(4)
	s_waitcnt lgkmcnt(3)
	s_waitcnt lgkmcnt(2)
	s_waitcnt lgkmcnt(3)
	s_waitcnt lgkmcnt(7)
	s_waitcnt lgkmcnt(6)
	s_waitcnt lgkmcnt(5)
	s_waitcnt lgkmcnt(4)
	s_waitcnt lgkmcnt(3)
	v_mov_b32_e32 v186, v128
	s_waitcnt lgkmcnt(2)
	v_mov_b32_e32 v184, v129
	s_waitcnt lgkmcnt(2)
	v_mov_b32_e32 v180, v130
	s_waitcnt lgkmcnt(1)
	v_mov_b32_e32 v178, v131
	s_waitcnt lgkmcnt(2)
	s_waitcnt lgkmcnt(1)
	v_mov_b32_e32 v174, v132
	s_waitcnt lgkmcnt(0)
	v_mov_b32_e32 v182, v133
	v_mov_b32_e32 v176, v134
	v_mov_b32_e32 v172, v135
	s_cbranch_scc1 .LBB0_319
	s_andn2_b64 vcc, exec, s[54:55]
	s_cbranch_vccz .LBB0_328

.LBB0_747:
	s_cmp_lt_i32 s60, 7
	s_cselect_b64 s[6:7], -1, 0
	s_and_b64 s[8:9], s[6:7], s[4:5]
	s_andn2_b64 vcc, exec, s[8:9]
	s_cbranch_vccnz .LBB0_766
	s_cmpk_gt_i32 s2, 0x1b7f
	s_cbranch_scc1 .LBB0_766
	v_mbcnt_hi_u32_b32 v0, -1, v228
	v_lshl_add_u32 v0, s71, 6, v0
	s_and_b32 s98, s2, 7
	s_lshr_b32 s99, s2, 3
	s_and_b32 s99, s99, 7
	s_sub_u32 s99, 7, s99
	s_mul_i32 s98, s98, 40
	s_add_u32 s98, s98, s99
	s_lshl_b32 s98, s98, 8
	s_add_u32 s100, s30, 0x3200000
	s_addc_u32 s101, s31, 0
	v_mov_b32_e32 v60, 0x358637bd
	v_add_u32_e32 v1, 0, v0
	v_lshrrev_b32_e32 v2, 8, v1
	v_lshlrev_b32_e32 v2, 11, v2
	v_and_b32_e32 v3, 0xff, v1
	v_add3_u32 v2, v2, v3, s98
	v_lshlrev_b32_e32 v2, 6, v2
	global_load_dwordx4 v[4:7], v2, s[100:101] offset:0
	global_load_dwordx4 v[8:11], v2, s[100:101] offset:16
	global_load_dwordx4 v[12:15], v2, s[100:101] offset:32
	global_load_dwordx4 v[16:19], v2, s[100:101] offset:48
	v_add_u32_e32 v21, 512, v0
	v_lshrrev_b32_e32 v22, 8, v21
	v_lshlrev_b32_e32 v22, 11, v22
	v_and_b32_e32 v23, 0xff, v21
	v_add3_u32 v22, v22, v23, s98
	v_lshlrev_b32_e32 v22, 6, v22
	global_load_dwordx4 v[24:27], v22, s[100:101] offset:0
	global_load_dwordx4 v[28:31], v22, s[100:101] offset:16
	global_load_dwordx4 v[32:35], v22, s[100:101] offset:32
	global_load_dwordx4 v[36:39], v22, s[100:101] offset:48
	s_cmp_lt_u32 s71, 4
	s_cbranch_scc0 .Lrs_skip_3200000
	v_add_u32_e32 v41, 1024, v0
	v_lshrrev_b32_e32 v42, 8, v41
	v_lshlrev_b32_e32 v42, 11, v42
	v_and_b32_e32 v43, 0xff, v41
	v_add3_u32 v42, v42, v43, s98
	v_lshlrev_b32_e32 v42, 6, v42
	global_load_dwordx4 v[44:47], v42, s[100:101] offset:0
	global_load_dwordx4 v[48:51], v42, s[100:101] offset:16
	global_load_dwordx4 v[52:55], v42, s[100:101] offset:32
	global_load_dwordx4 v[56:59], v42, s[100:101] offset:48

.Lrs_done_3200000:
	s_waitcnt lgkmcnt(0)
	s_add_u32 s40, s30, 0x1a00000
	s_addc_u32 s41, s31, 0
	v_mbcnt_hi_u32_b32 v9, -1, v228
	s_lshl_b32 s42, s71, 10
	v_lshl_add_u32 v0, v9, 4, s42
	s_waitcnt lgkmcnt(0)
	v_add_u32_e32 v1, 0x2000, v0
	v_ashrrev_i32_e32 v2, 31, v1
	v_lshrrev_b32_e32 v2, 22, v2
	v_add_u32_e32 v2, v1, v2
	v_ashrrev_i32_e32 v8, 10, v2
	v_mul_i32_i24_e32 v2, 0x400, v8
	v_sub_u32_e32 v1, v1, v2
	v_lshrrev_b32_e32 v2, 4, v1
	v_bitop3_b32 v1, v2, v1, 32 bitop3:0x6c
	v_ashrrev_i32_e32 v2, 31, v1
	v_lshrrev_b32_e32 v2, 26, v2
	v_add_u32_e32 v2, v1, v2
	v_ashrrev_i32_e32 v10, 6, v2
	v_lshlrev_b32_e32 v3, 3, v8
	v_and_b32_e32 v2, 0xffc0, v2
	v_and_b32_e32 v3, -16, v3
	v_sub_u32_e32 v1, v1, v2
	v_add_u32_e32 v3, v10, v3
	v_lshrrev_b16_e32 v2, 7, v1
	v_and_b32_e32 v4, 3, v10
	s_mov_b32 s4, 0x1fffe0
	v_lshrrev_b32_e32 v5, 2, v3
	v_lshlrev_b32_e32 v6, 1, v3
	v_and_b32_e32 v2, 1, v2
	v_and_or_b32 v4, v3, s4, v4
	v_and_b32_e32 v5, 4, v5
	v_and_b32_e32 v6, 24, v6
	v_add_u16_e32 v1, v1, v2
	v_mov_b32_e32 v2, 1
	v_or3_b32 v4, v4, v5, v6
	v_lshlrev_b32_e32 v5, 5, v8
	v_ashrrev_i16_sdwa v1, v2, sext(v1) dst_sel:DWORD dst_unused:UNUSED_PAD src0_sel:DWORD src1_sel:BYTE_0
	v_and_b32_e32 v5, 32, v5
	v_bfe_i32 v11, v1, 0, 16
	v_add_lshl_u32 v1, v5, v11, 1
	v_lshl_add_u32 v128, v4, 11, v1
	v_lshl_add_u32 v130, v3, 11, v1
	v_ashrrev_i32_e32 v1, 31, v0
	v_lshrrev_b32_e32 v1, 22, v1
	v_add_u32_e32 v1, v0, v1
	v_ashrrev_i32_e32 v12, 10, v1
	v_mul_i32_i24_e32 v1, 0x400, v12
	v_sub_u32_e32 v0, v0, v1
	v_lshrrev_b32_e32 v1, 4, v0
	v_bitop3_b32 v0, v1, v0, 32 bitop3:0x6c
	v_ashrrev_i32_e32 v1, 31, v0
	v_lshrrev_b32_e32 v1, 26, v1
	v_add_u32_e32 v1, v0, v1
	v_lshlrev_b32_e32 v3, 3, v12
	v_ashrrev_i32_e32 v13, 6, v1
	v_and_b32_e32 v3, -16, v3
	v_add_u32_e32 v3, v13, v3
	v_and_b32_e32 v4, 3, v13
	s_ashr_i32 s43, s2, 31
	v_and_or_b32 v4, v3, s4, v4
	s_lshr_b32 s4, s43, 29
	s_add_i32 s4, s2, s4
	s_ashr_i32 s6, s4, 3
	s_and_b32 s4, s4, -8
	s_lshr_b32 s5, s3, 8
	s_sub_i32 s4, s2, s4
	s_cmp_lt_i32 s4, 0
	s_movk_i32 s44, 0x371
	s_cselect_b32 s7, s44, 0x370
	s_mul_i32 s4, s4, s7
	s_add_i32 s4, s4, s6
	s_mul_hi_i32 s6, s4, 0x2e8ba2e9
	s_lshr_b32 s7, s6, 31
	s_ashr_i32 s6, s6, 5
	s_add_i32 s6, s6, s7
	s_mul_i32 s7, s6, 0xb0
	s_sub_i32 s7, s4, s7
	s_sext_i32_i16 s4, s7
	s_bfe_u32 s4, s4, 0x3001c
	s_add_i32 s12, s7, s4
	s_sext_i32_i16 s4, s12
	s_and_b32 s12, s12, 0xfff8
	s_sub_i32 s7, s7, s12
	s_lshl_b32 s6, s6, 3
	s_sext_i32_i16 s7, s7
	s_add_i32 s6, s6, s7
	s_mul_hi_i32 s7, s6, 0x66666667
	s_lshr_b32 s12, s7, 31
	s_ashr_i32 s7, s7, 4
	s_add_i32 s7, s7, s12
	s_mul_i32 s7, s7, 40
	s_sub_i32 s7, s6, s7
	s_lshl_b32 s7, s7, 1
	s_sub_i32 s6, s6, s7
	v_lshrrev_b32_e32 v5, 2, v3
	v_lshlrev_b32_e32 v6, 1, v3
	v_and_b32_e32 v1, 0xc0, v1
	s_lshr_b32 s4, s4, 3
	s_add_i32 s26, s6, 39
	v_and_b32_e32 v5, 4, v5
	v_and_b32_e32 v6, 24, v6
	v_sub_u32_e32 v0, v0, v1
	s_ashr_i32 s27, s26, 31
	s_bfe_i64 s[12:13], s[4:5], 0x100000
	v_or3_b32 v4, v4, v5, v6
	v_lshlrev_b32_e32 v5, 5, v12
	v_ashrrev_i16_sdwa v0, v2, sext(v0) dst_sel:DWORD dst_unused:UNUSED_PAD src0_sel:DWORD src1_sel:BYTE_0
	s_lshl_b64 s[6:7], s[26:27], 19
	s_lshl_b64 s[12:13], s[12:13], 19
	v_and_b32_e32 v5, 32, v5
	v_bfe_i32 v14, v0, 0, 16
	s_add_u32 s36, s40, s12
	v_add_lshl_u32 v0, v5, v14, 1
	s_addc_u32 s37, s41, s13
	s_add_i32 s27, s42, 0
	v_lshl_add_u32 v132, v4, 11, v0
	s_add_i32 m0, s27, 0x10000
	v_lshl_add_u32 v134, v3, 11, v0
	global_load_lds_dwordx4 v132, s[36:37]
	s_add_i32 m0, s27, 0x12000
	s_add_u32 s12, s36, 0x40000
	global_load_lds_dwordx4 v128, s[36:37]
	s_addc_u32 s13, s37, 0
	s_add_i32 m0, s27, 0x14000
	v_mov_b32_e32 v133, 0
	global_load_lds_dwordx4 v132, s[12:13]
	s_add_i32 m0, s27, 0x16000
	s_add_u32 s38, s62, s6
	s_addc_u32 s39, s63, s7
	s_add_i32 s45, s27, 0x2000
	global_load_lds_dwordx4 v128, s[12:13]
	s_mov_b32 m0, s27
	s_add_u32 s6, s38, 0x40000
	global_load_lds_dwordx4 v134, s[38:39]
	s_mov_b32 m0, s45
	s_addc_u32 s7, s39, 0
	s_add_i32 s46, s27, 0x4000
	global_load_lds_dwordx4 v130, s[38:39]
	s_mov_b32 m0, s46
	s_add_i32 s47, s27, 0x6000
	global_load_lds_dwordx4 v134, s[6:7]
	s_mov_b32 m0, s47
	v_mov_b32_e32 v129, v133
	global_load_lds_dwordx4 v130, s[6:7]
	v_mov_b32_e32 v135, v133
	v_mov_b32_e32 v131, v133
	s_cmp_eq_u32 s5, 1
	s_mov_b32 s48, 0
	v_lshl_add_u64 v[6:7], s[36:37], 0, v[132:133]
	v_lshl_add_u64 v[4:5], s[36:37], 0, v[128:129]
	v_lshl_add_u64 v[0:1], s[38:39], 0, v[134:135]
	s_cselect_b64 s[12:13], -1, 0
	s_cmp_lg_u32 s5, 1
	v_lshl_add_u64 v[2:3], s[38:39], 0, v[130:131]
	s_cbranch_scc1 .LBB0_751
	s_barrier

.LBB0_762:
	s_mul_i32 s98, s26, 0x667
	s_lshr_b32 s98, s98, 16
	s_mul_i32 s98, s98, 40
	s_sub_u32 s98, s26, s98
	s_lshr_b32 s98, s98, 3
	s_lshl_b32 s98, s98, 10
	s_add_u32 s98, s98, 0x20800
	v_mov_b32_e32 v179, v153
	v_lshl_add_u32 v179, v179, 2, s98
	ds_read_b32 v147, v179 offset:0
	ds_read_b32 v149, v179 offset:128
	ds_read_b32 v151, v179 offset:64
	ds_read_b32 v155, v179 offset:512
	ds_read_b32 v159, v179 offset:192
	ds_read_b32 v163, v179 offset:576
	ds_read_b32 v167, v179 offset:640
	ds_read_b32 v169, v179 offset:704
	s_waitcnt lgkmcnt(0)
	v_lshl_add_u32 v168, s26, 8, v153
	v_or_b32_e32 v166, 16, v168
	v_or_b32_e32 v162, 32, v168
	v_or_b32_e32 v158, 48, v168
	v_add_u32_e32 v154, 0x80, v168
	v_add_u32_e32 v150, 0x90, v168
	v_add_u32_e32 v148, 0xa0, v168
	v_add_u32_e32 v146, 0xb0, v168
	s_and_b64 vcc, exec, s[6:7]
	s_waitcnt lgkmcnt(0)
	s_waitcnt lgkmcnt(0)
	v_mov_b32_e32 v176, v147
	v_pk_mul_f32 v[124:125], v[124:125], v[176:177] op_sel_hi:[1,0]
	v_exp_f32_e64 v184, -v124
	v_exp_f32_e64 v185, -v125
	v_pk_mul_f32 v[126:127], v[126:127], v[176:177] op_sel_hi:[1,0]
	v_pk_mul_f32 v[122:123], v[122:123], v[176:177] op_sel_hi:[1,0]
	v_pk_mul_f32 v[120:121], v[120:121], v[176:177] op_sel_hi:[1,0]
	v_pk_mul_f32 v[116:117], v[116:117], v[176:177] op_sel_hi:[1,0]
	v_pk_mul_f32 v[118:119], v[118:119], v[176:177] op_sel_hi:[1,0]
	v_pk_mul_f32 v[112:113], v[112:113], v[176:177] op_sel_hi:[1,0]
	v_pk_mul_f32 v[114:115], v[114:115], v[176:177] op_sel_hi:[1,0]
	v_pk_add_f32 v[176:177], v[184:185], 1.0 op_sel_hi:[1,0]
	v_exp_f32_e64 v184, -v126
	v_exp_f32_e64 v185, -v127
	v_pk_mul_f32 v[116:117], v[124:125], v[116:117]
	v_pk_add_f32 v[124:125], v[184:185], 1.0 op_sel_hi:[1,0]
	v_rcp_f32_e32 v124, v124
	v_rcp_f32_e32 v125, v125
	v_rcp_f32_e32 v176, v176
	v_rcp_f32_e32 v177, v177
	s_waitcnt lgkmcnt(3)
	s_waitcnt lgkmcnt(2)
	v_pk_mul_f32 v[118:119], v[126:127], v[118:119]
	v_exp_f32_e64 v126, -v120
	v_exp_f32_e64 v127, -v121
	v_pk_mul_f32 v[118:119], v[118:119], v[124:125]
	v_exp_f32_e64 v124, -v122
	v_exp_f32_e64 v125, -v123
	s_waitcnt lgkmcnt(3)
	s_waitcnt lgkmcnt(2)
	v_pk_mul_f32 v[116:117], v[116:117], v[176:177]
	v_pk_mul_f32 v[114:115], v[122:123], v[114:115]
	v_cvt_pk_bf16_f32 v116, v116, v117
	v_cvt_pk_bf16_f32 v117, v118, v119
	v_pk_add_f32 v[118:119], v[126:127], 1.0 op_sel_hi:[1,0]
	v_pk_add_f32 v[122:123], v[124:125], 1.0 op_sel_hi:[1,0]
	v_rcp_f32_e32 v118, v118
	v_rcp_f32_e32 v119, v119
	s_waitcnt lgkmcnt(3)
	s_waitcnt lgkmcnt(2)
	v_rcp_f32_e32 v122, v122
	v_rcp_f32_e32 v123, v123
	s_waitcnt lgkmcnt(1)
	s_waitcnt lgkmcnt(0)
	v_mov_b32_e32 v180, v149
	v_pk_mul_f32 v[112:113], v[120:121], v[112:113]
	v_mov_b32_e32 v178, v151
	v_pk_mul_f32 v[112:113], v[112:113], v[118:119]
	v_mov_b32_e32 v164, v155
	v_lshl_add_u32 v182, s56, 7, v171
	v_cvt_pk_bf16_f32 v118, v112, v113
	v_pk_mul_f32 v[112:113], v[114:115], v[122:123]
	v_ashrrev_i32_e32 v183, 31, v182
	v_cvt_pk_bf16_f32 v119, v112, v113
	v_mov_b64_e32 v[112:113], s[24:25]
	v_mad_i64_i32 v[120:121], s[4:5], v168, s55, v[112:113]
	v_lshlrev_b64 v[114:115], 1, v[182:183]
	v_lshl_add_u64 v[120:121], v[120:121], 0, v[114:115]
	v_pk_mul_f32 v[108:109], v[108:109], v[178:179] op_sel_hi:[1,0]
	global_store_dwordx4 v[120:121], v[116:119], off
	v_pk_mul_f32 v[110:111], v[110:111], v[178:179] op_sel_hi:[1,0]
	v_pk_mul_f32 v[100:101], v[100:101], v[178:179] op_sel_hi:[1,0]
	v_exp_f32_e64 v116, -v108
	v_exp_f32_e64 v117, -v109
	v_pk_mul_f32 v[118:119], v[96:97], v[178:179] op_sel_hi:[1,0]
	v_pk_mul_f32 v[100:101], v[108:109], v[100:101]
	v_pk_mul_f32 v[102:103], v[102:103], v[178:179] op_sel_hi:[1,0]
	v_pk_add_f32 v[96:97], v[116:117], 1.0 op_sel_hi:[1,0]
	v_exp_f32_e64 v116, -v110
	v_rcp_f32_e32 v96, v96
	v_rcp_f32_e32 v97, v97
	v_exp_f32_e64 v117, -v111
	v_pk_mul_f32 v[106:107], v[106:107], v[178:179] op_sel_hi:[1,0]
	v_pk_mul_f32 v[104:105], v[104:105], v[178:179] op_sel_hi:[1,0]
	v_pk_mul_f32 v[96:97], v[100:101], v[96:97]
	v_pk_add_f32 v[100:101], v[116:117], 1.0 op_sel_hi:[1,0]
	v_pk_mul_f32 v[102:103], v[110:111], v[102:103]
	v_rcp_f32_e32 v100, v100
	v_rcp_f32_e32 v101, v101
	v_exp_f32_e64 v108, -v104
	v_exp_f32_e64 v109, -v105
	v_pk_mul_f32 v[98:99], v[98:99], v[178:179] op_sel_hi:[1,0]
	v_pk_mul_f32 v[100:101], v[102:103], v[100:101]
	v_exp_f32_e64 v102, -v106
	v_exp_f32_e64 v103, -v107
	v_cvt_pk_bf16_f32 v96, v96, v97
	v_cvt_pk_bf16_f32 v97, v100, v101
	v_pk_add_f32 v[100:101], v[108:109], 1.0 op_sel_hi:[1,0]
	v_pk_mul_f32 v[106:107], v[106:107], v[98:99]
	v_pk_add_f32 v[98:99], v[102:103], 1.0 op_sel_hi:[1,0]
	v_rcp_f32_e32 v100, v100
	v_rcp_f32_e32 v101, v101
	v_rcp_f32_e32 v102, v98
	v_rcp_f32_e32 v103, v99
	v_pk_mul_f32 v[98:99], v[104:105], v[118:119]
	v_pk_mul_f32 v[92:93], v[92:93], v[180:181] op_sel_hi:[1,0]
	v_pk_mul_f32 v[98:99], v[98:99], v[100:101]
	v_pk_mul_f32 v[100:101], v[106:107], v[102:103]
	v_cvt_pk_bf16_f32 v98, v98, v99
	v_pk_mul_f32 v[94:95], v[94:95], v[180:181] op_sel_hi:[1,0]
	v_cvt_pk_bf16_f32 v99, v100, v101
	v_mad_i64_i32 v[100:101], s[4:5], v166, s55, v[112:113]
	v_lshl_add_u64 v[100:101], v[100:101], 0, v[114:115]
	global_store_dwordx4 v[100:101], v[96:99], off
	v_pk_mul_f32 v[84:85], v[84:85], v[180:181] op_sel_hi:[1,0]
	v_pk_mul_f32 v[86:87], v[86:87], v[180:181] op_sel_hi:[1,0]
	v_exp_f32_e64 v96, -v92
	v_exp_f32_e64 v97, -v93
	v_pk_mul_f32 v[98:99], v[80:81], v[180:181] op_sel_hi:[1,0]
	v_pk_mul_f32 v[84:85], v[92:93], v[84:85]
	v_pk_mul_f32 v[90:91], v[90:91], v[180:181] op_sel_hi:[1,0]
	v_pk_add_f32 v[80:81], v[96:97], 1.0 op_sel_hi:[1,0]
	v_exp_f32_e64 v96, -v94
	v_rcp_f32_e32 v80, v80
	v_rcp_f32_e32 v81, v81
	v_exp_f32_e64 v97, -v95
	v_pk_mul_f32 v[88:89], v[88:89], v[180:181] op_sel_hi:[1,0]
	v_pk_mul_f32 v[86:87], v[94:95], v[86:87]
	v_pk_mul_f32 v[80:81], v[84:85], v[80:81]
	v_pk_add_f32 v[84:85], v[96:97], 1.0 op_sel_hi:[1,0]
	v_exp_f32_e64 v92, -v88
	v_rcp_f32_e32 v84, v84
	v_rcp_f32_e32 v85, v85
	v_exp_f32_e64 v93, -v89
	v_pk_mul_f32 v[82:83], v[82:83], v[180:181] op_sel_hi:[1,0]
	v_cvt_pk_bf16_f32 v80, v80, v81
	v_pk_mul_f32 v[84:85], v[86:87], v[84:85]
	v_exp_f32_e64 v86, -v90
	v_exp_f32_e64 v87, -v91
	v_cvt_pk_bf16_f32 v81, v84, v85
	v_pk_add_f32 v[84:85], v[92:93], 1.0 op_sel_hi:[1,0]
	v_pk_mul_f32 v[90:91], v[90:91], v[82:83]
	v_pk_add_f32 v[82:83], v[86:87], 1.0 op_sel_hi:[1,0]
	v_rcp_f32_e32 v84, v84
	v_rcp_f32_e32 v85, v85
	v_rcp_f32_e32 v86, v82
	v_rcp_f32_e32 v87, v83
	v_mov_b32_e32 v170, v159
	v_pk_mul_f32 v[82:83], v[88:89], v[98:99]
	v_pk_mul_f32 v[60:61], v[60:61], v[164:165] op_sel_hi:[1,0]
	v_pk_mul_f32 v[82:83], v[82:83], v[84:85]
	v_pk_mul_f32 v[84:85], v[90:91], v[86:87]
	v_cvt_pk_bf16_f32 v82, v82, v83
	v_pk_mul_f32 v[76:77], v[76:77], v[170:171] op_sel_hi:[1,0]
	v_cvt_pk_bf16_f32 v83, v84, v85
	v_mad_i64_i32 v[84:85], s[4:5], v162, s55, v[112:113]
	v_lshl_add_u64 v[84:85], v[84:85], 0, v[114:115]
	global_store_dwordx4 v[84:85], v[80:83], off
	v_pk_mul_f32 v[78:79], v[78:79], v[170:171] op_sel_hi:[1,0]
	v_pk_mul_f32 v[68:69], v[68:69], v[170:171] op_sel_hi:[1,0]
	v_exp_f32_e64 v80, -v76
	v_exp_f32_e64 v81, -v77
	v_pk_mul_f32 v[82:83], v[64:65], v[170:171] op_sel_hi:[1,0]
	v_pk_mul_f32 v[68:69], v[76:77], v[68:69]
	v_pk_mul_f32 v[70:71], v[70:71], v[170:171] op_sel_hi:[1,0]
	v_pk_add_f32 v[64:65], v[80:81], 1.0 op_sel_hi:[1,0]
	v_exp_f32_e64 v80, -v78
	v_rcp_f32_e32 v64, v64
	v_rcp_f32_e32 v65, v65
	v_exp_f32_e64 v81, -v79
	v_pk_mul_f32 v[74:75], v[74:75], v[170:171] op_sel_hi:[1,0]
	v_pk_mul_f32 v[72:73], v[72:73], v[170:171] op_sel_hi:[1,0]
	v_pk_mul_f32 v[64:65], v[68:69], v[64:65]
	v_pk_add_f32 v[68:69], v[80:81], 1.0 op_sel_hi:[1,0]
	v_pk_mul_f32 v[70:71], v[78:79], v[70:71]
	v_rcp_f32_e32 v68, v68
	v_rcp_f32_e32 v69, v69
	v_exp_f32_e64 v76, -v72
	v_exp_f32_e64 v77, -v73
	v_pk_mul_f32 v[66:67], v[66:67], v[170:171] op_sel_hi:[1,0]
	v_pk_mul_f32 v[68:69], v[70:71], v[68:69]
	v_exp_f32_e64 v70, -v74
	v_exp_f32_e64 v71, -v75
	v_cvt_pk_bf16_f32 v64, v64, v65
	v_cvt_pk_bf16_f32 v65, v68, v69
	v_pk_add_f32 v[68:69], v[76:77], 1.0 op_sel_hi:[1,0]
	v_pk_mul_f32 v[74:75], v[74:75], v[66:67]
	v_pk_add_f32 v[66:67], v[70:71], 1.0 op_sel_hi:[1,0]
	v_rcp_f32_e32 v68, v68
	v_rcp_f32_e32 v69, v69
	v_rcp_f32_e32 v70, v66
	v_rcp_f32_e32 v71, v67
	v_pk_mul_f32 v[66:67], v[72:73], v[82:83]
	v_pk_mul_f32 v[62:63], v[62:63], v[164:165] op_sel_hi:[1,0]
	v_pk_mul_f32 v[66:67], v[66:67], v[68:69]
	v_pk_mul_f32 v[68:69], v[74:75], v[70:71]
	v_cvt_pk_bf16_f32 v66, v66, v67
	v_pk_mul_f32 v[52:53], v[52:53], v[164:165] op_sel_hi:[1,0]
	v_cvt_pk_bf16_f32 v67, v68, v69
	v_mad_i64_i32 v[68:69], s[4:5], v158, s55, v[112:113]
	v_lshl_add_u64 v[68:69], v[68:69], 0, v[114:115]
	global_store_dwordx4 v[68:69], v[64:67], off
	v_pk_mul_f32 v[52:53], v[60:61], v[52:53]
	v_exp_f32_e64 v64, -v60
	v_exp_f32_e64 v65, -v61
	v_pk_mul_f32 v[66:67], v[48:49], v[164:165] op_sel_hi:[1,0]
	v_pk_mul_f32 v[54:55], v[54:55], v[164:165] op_sel_hi:[1,0]
	s_waitcnt lgkmcnt(0)
	v_pk_add_f32 v[48:49], v[64:65], 1.0 op_sel_hi:[1,0]
	v_exp_f32_e64 v64, -v62
	v_rcp_f32_e32 v48, v48
	v_rcp_f32_e32 v49, v49
	v_exp_f32_e64 v65, -v63
	v_pk_mul_f32 v[58:59], v[58:59], v[164:165] op_sel_hi:[1,0]
	v_pk_mul_f32 v[56:57], v[56:57], v[164:165] op_sel_hi:[1,0]
	v_pk_mul_f32 v[48:49], v[52:53], v[48:49]
	v_pk_add_f32 v[52:53], v[64:65], 1.0 op_sel_hi:[1,0]
	v_pk_mul_f32 v[54:55], v[62:63], v[54:55]
	v_rcp_f32_e32 v52, v52
	v_rcp_f32_e32 v53, v53
	v_exp_f32_e64 v60, -v56
	v_exp_f32_e64 v61, -v57
	v_pk_mul_f32 v[52:53], v[54:55], v[52:53]
	v_exp_f32_e64 v54, -v58
	v_exp_f32_e64 v55, -v59
	v_pk_mul_f32 v[50:51], v[50:51], v[164:165] op_sel_hi:[1,0]
	v_cvt_pk_bf16_f32 v48, v48, v49
	v_cvt_pk_bf16_f32 v49, v52, v53
	v_pk_add_f32 v[52:53], v[60:61], 1.0 op_sel_hi:[1,0]
	v_pk_mul_f32 v[58:59], v[58:59], v[50:51]
	v_pk_add_f32 v[50:51], v[54:55], 1.0 op_sel_hi:[1,0]
	s_waitcnt lgkmcnt(0)
	v_rcp_f32_e32 v52, v52
	v_rcp_f32_e32 v53, v53
	v_rcp_f32_e32 v54, v50
	v_rcp_f32_e32 v55, v51
	v_mov_b32_e32 v160, v163
	v_pk_mul_f32 v[50:51], v[56:57], v[66:67]
	v_pk_mul_f32 v[50:51], v[50:51], v[52:53]
	v_pk_mul_f32 v[52:53], v[58:59], v[54:55]
	v_cvt_pk_bf16_f32 v50, v50, v51
	v_pk_mul_f32 v[44:45], v[44:45], v[160:161] op_sel_hi:[1,0]
	v_cvt_pk_bf16_f32 v51, v52, v53
	v_mad_i64_i32 v[52:53], s[4:5], v154, s55, v[112:113]
	v_lshl_add_u64 v[52:53], v[52:53], 0, v[114:115]
	global_store_dwordx4 v[52:53], v[48:51], off
	v_pk_mul_f32 v[46:47], v[46:47], v[160:161] op_sel_hi:[1,0]
	v_pk_mul_f32 v[36:37], v[36:37], v[160:161] op_sel_hi:[1,0]
	v_exp_f32_e64 v48, -v44
	v_exp_f32_e64 v49, -v45
	v_pk_mul_f32 v[50:51], v[32:33], v[160:161] op_sel_hi:[1,0]
	v_pk_mul_f32 v[36:37], v[44:45], v[36:37]
	v_pk_mul_f32 v[38:39], v[38:39], v[160:161] op_sel_hi:[1,0]
	v_pk_add_f32 v[32:33], v[48:49], 1.0 op_sel_hi:[1,0]
	v_exp_f32_e64 v48, -v46
	v_rcp_f32_e32 v32, v32
	v_rcp_f32_e32 v33, v33
	v_exp_f32_e64 v49, -v47
	s_waitcnt lgkmcnt(0)
	v_pk_mul_f32 v[42:43], v[42:43], v[160:161] op_sel_hi:[1,0]
	v_pk_mul_f32 v[32:33], v[36:37], v[32:33]
	v_pk_add_f32 v[36:37], v[48:49], 1.0 op_sel_hi:[1,0]
	v_pk_mul_f32 v[40:41], v[40:41], v[160:161] op_sel_hi:[1,0]
	v_rcp_f32_e32 v36, v36
	v_rcp_f32_e32 v37, v37
	v_pk_mul_f32 v[38:39], v[46:47], v[38:39]
	v_exp_f32_e64 v44, -v40
	v_exp_f32_e64 v45, -v41
	v_pk_mul_f32 v[36:37], v[38:39], v[36:37]
	v_exp_f32_e64 v38, -v42
	v_exp_f32_e64 v39, -v43
	v_pk_mul_f32 v[34:35], v[34:35], v[160:161] op_sel_hi:[1,0]
	v_cvt_pk_bf16_f32 v32, v32, v33
	v_cvt_pk_bf16_f32 v33, v36, v37
	v_pk_add_f32 v[36:37], v[44:45], 1.0 op_sel_hi:[1,0]
	v_pk_mul_f32 v[42:43], v[42:43], v[34:35]
	v_pk_add_f32 v[34:35], v[38:39], 1.0 op_sel_hi:[1,0]
	s_waitcnt lgkmcnt(0)
	v_rcp_f32_e32 v36, v36
	v_rcp_f32_e32 v37, v37
	v_rcp_f32_e32 v38, v34
	v_rcp_f32_e32 v39, v35
	v_mov_b32_e32 v156, v167
	v_pk_mul_f32 v[34:35], v[40:41], v[50:51]
	v_pk_mul_f32 v[34:35], v[34:35], v[36:37]
	v_pk_mul_f32 v[36:37], v[42:43], v[38:39]
	v_cvt_pk_bf16_f32 v34, v34, v35
	v_pk_mul_f32 v[28:29], v[28:29], v[156:157] op_sel_hi:[1,0]
	v_cvt_pk_bf16_f32 v35, v36, v37
	v_mad_i64_i32 v[36:37], s[4:5], v150, s55, v[112:113]
	v_lshl_add_u64 v[36:37], v[36:37], 0, v[114:115]
	global_store_dwordx4 v[36:37], v[32:35], off
	v_pk_mul_f32 v[30:31], v[30:31], v[156:157] op_sel_hi:[1,0]
	v_pk_mul_f32 v[20:21], v[20:21], v[156:157] op_sel_hi:[1,0]
	v_exp_f32_e64 v32, -v28
	v_exp_f32_e64 v33, -v29
	v_pk_mul_f32 v[34:35], v[16:17], v[156:157] op_sel_hi:[1,0]
	v_pk_mul_f32 v[20:21], v[28:29], v[20:21]
	v_pk_mul_f32 v[22:23], v[22:23], v[156:157] op_sel_hi:[1,0]
	v_pk_add_f32 v[16:17], v[32:33], 1.0 op_sel_hi:[1,0]
	v_exp_f32_e64 v32, -v30
	v_rcp_f32_e32 v16, v16
	v_rcp_f32_e32 v17, v17
	v_exp_f32_e64 v33, -v31
	s_waitcnt lgkmcnt(0)
	v_pk_mul_f32 v[26:27], v[26:27], v[156:157] op_sel_hi:[1,0]
	v_pk_mul_f32 v[16:17], v[20:21], v[16:17]
	v_pk_add_f32 v[20:21], v[32:33], 1.0 op_sel_hi:[1,0]
	v_pk_mul_f32 v[24:25], v[24:25], v[156:157] op_sel_hi:[1,0]
	v_rcp_f32_e32 v20, v20
	v_rcp_f32_e32 v21, v21
	v_pk_mul_f32 v[22:23], v[30:31], v[22:23]
	v_exp_f32_e64 v28, -v24
	v_exp_f32_e64 v29, -v25
	v_pk_mul_f32 v[20:21], v[22:23], v[20:21]
	v_exp_f32_e64 v22, -v26
	v_exp_f32_e64 v23, -v27
	v_pk_mul_f32 v[18:19], v[18:19], v[156:157] op_sel_hi:[1,0]
	v_cvt_pk_bf16_f32 v16, v16, v17
	v_cvt_pk_bf16_f32 v17, v20, v21
	v_pk_add_f32 v[20:21], v[28:29], 1.0 op_sel_hi:[1,0]
	v_pk_mul_f32 v[26:27], v[26:27], v[18:19]
	v_pk_add_f32 v[18:19], v[22:23], 1.0 op_sel_hi:[1,0]
	s_waitcnt lgkmcnt(0)
	v_rcp_f32_e32 v20, v20
	v_rcp_f32_e32 v21, v21
	v_rcp_f32_e32 v22, v18
	v_rcp_f32_e32 v23, v19
	v_mov_b32_e32 v152, v169
	v_pk_mul_f32 v[18:19], v[24:25], v[34:35]
	v_pk_mul_f32 v[12:13], v[12:13], v[152:153] op_sel_hi:[1,0]
	v_pk_mul_f32 v[18:19], v[18:19], v[20:21]
	v_pk_mul_f32 v[20:21], v[26:27], v[22:23]
	v_cvt_pk_bf16_f32 v18, v18, v19
	v_pk_mul_f32 v[14:15], v[14:15], v[152:153] op_sel_hi:[1,0]
	v_cvt_pk_bf16_f32 v19, v20, v21
	v_mad_i64_i32 v[20:21], s[4:5], v148, s55, v[112:113]
	v_lshl_add_u64 v[20:21], v[20:21], 0, v[114:115]
	global_store_dwordx4 v[20:21], v[16:19], off
	v_pk_mul_f32 v[4:5], v[4:5], v[152:153] op_sel_hi:[1,0]
	v_pk_mul_f32 v[6:7], v[6:7], v[152:153] op_sel_hi:[1,0]
	v_exp_f32_e64 v16, -v12
	v_exp_f32_e64 v17, -v13
	v_pk_mul_f32 v[18:19], v[0:1], v[152:153] op_sel_hi:[1,0]
	v_pk_mul_f32 v[4:5], v[12:13], v[4:5]
	v_pk_mul_f32 v[10:11], v[10:11], v[152:153] op_sel_hi:[1,0]
	v_pk_add_f32 v[0:1], v[16:17], 1.0 op_sel_hi:[1,0]
	v_exp_f32_e64 v16, -v14
	v_rcp_f32_e32 v0, v0
	v_rcp_f32_e32 v1, v1
	v_exp_f32_e64 v17, -v15
	v_pk_mul_f32 v[8:9], v[8:9], v[152:153] op_sel_hi:[1,0]
	v_pk_mul_f32 v[6:7], v[14:15], v[6:7]
	v_pk_mul_f32 v[0:1], v[4:5], v[0:1]
	v_pk_add_f32 v[4:5], v[16:17], 1.0 op_sel_hi:[1,0]
	v_exp_f32_e64 v12, -v8
	v_rcp_f32_e32 v4, v4
	v_rcp_f32_e32 v5, v5
	v_exp_f32_e64 v13, -v9
	v_pk_mul_f32 v[2:3], v[2:3], v[152:153] op_sel_hi:[1,0]
	v_cvt_pk_bf16_f32 v0, v0, v1
	v_pk_mul_f32 v[4:5], v[6:7], v[4:5]
	v_exp_f32_e64 v6, -v10
	v_exp_f32_e64 v7, -v11
	v_cvt_pk_bf16_f32 v1, v4, v5
	v_pk_add_f32 v[4:5], v[12:13], 1.0 op_sel_hi:[1,0]
	v_pk_mul_f32 v[10:11], v[10:11], v[2:3]
	v_pk_add_f32 v[2:3], v[6:7], 1.0 op_sel_hi:[1,0]
	v_rcp_f32_e32 v4, v4
	v_rcp_f32_e32 v5, v5
	v_rcp_f32_e32 v6, v2
	v_rcp_f32_e32 v7, v3
	v_pk_mul_f32 v[2:3], v[8:9], v[18:19]
	s_nop 0
	v_pk_mul_f32 v[2:3], v[2:3], v[4:5]
	v_pk_mul_f32 v[4:5], v[10:11], v[6:7]
	v_cvt_pk_bf16_f32 v2, v2, v3
	s_nop 0
	v_cvt_pk_bf16_f32 v3, v4, v5
	v_mad_i64_i32 v[4:5], s[4:5], v146, s55, v[112:113]
	v_lshl_add_u64 v[4:5], v[4:5], 0, v[114:115]
	s_mov_b64 s[4:5], -1
	global_store_dwordx4 v[4:5], v[0:3], off
	s_cbranch_vccnz .LBB0_753
	s_andn2_b64 vcc, exec, s[12:13]
	s_cbranch_vccnz .LBB0_752
	s_barrier
	s_branch .LBB0_752
